# a_in tile order: every round works on one 4096-token block (all XCDs), blocks in ascending order = the order the sgu phase reads them
# speedup vs baseline: 1.0093x; 1.0055x over previous
.LBB0_9:
	v_cmp_gt_u32_e32 vcc, 0x100, v157
	s_cmp_eq_u32 s3, 1
	s_cselect_b64 s[64:65], -1, 0
	s_nop 0
	s_and_b64 vcc, vcc, s[64:65]
	s_and_saveexec_b64 s[62:63], vcc
	s_cbranch_execz .LBB0_15
	s_load_dwordx2 s[12:13], s[44:45], 0x68
	s_load_dwordx4 s[28:31], s[44:45], 0x58
	v_lshrrev_b32_e32 v2, 6, v157
	v_add_u32_e32 v2, 0, v2
	v_and_b32_e32 v68, 15, v157
	v_bfe_u32 v69, v157, 4, 2
	s_lshl_b32 s65, s2, 2
	v_readfirstlane_b32 s64, v2
	v_lshlrev_b32_e32 v128, 10, v68
	v_lshlrev_b32_e32 v129, 4, v69
	v_lshlrev_b32_e32 v133, 14, v69
	v_lshlrev_b32_e32 v131, 13, v68
	s_add_i32 s64, s64, s65
	s_lshl_b32 s65, s42, 2
	v_lshl_add_u32 v128, v69, 4, v128
	v_lshl_add_u32 v133, v68, 4, v133
	v_lshl_add_u32 v131, v69, 3, v131
	s_nop 0
	v_add_u32_e32 v132, 0x1000, v131
	s_waitcnt lgkmcnt(0)

.LBB0_241:
	s_ashr_i32 s10, s12, 3
	s_add_i32 s10, s14, s10
	s_ashr_i32 s11, s10, 31
	s_lshr_b32 s11, s11, 27
	s_add_i32 s11, s10, s11
	s_ashr_i32 s12, s11, 5
	s_andn2_b32 s11, s11, 31
	s_sub_i32 s10, s10, s11
	s_bfe_u32 s11, s10, 0x10007
	s_add_i32 s11, s10, s11
	s_bfe_i32 s13, s11, 0x80000
	s_and_b32 s11, s11, 0xfe
	s_sub_i32 s10, s10, s11
	s_lshl_b32 s12, s12, 1
	s_sext_i32_i16 s13, s13
	s_sext_i32_i8 s10, s10
	s_add_i32 s14, s12, s10
	s_ashr_i32 s20, s13, 1
	s_cmp_eq_u32 s42, 0x100
	s_cbranch_scc0 .Lwgm_p_1
	s_lshr_b32 s99, s2, 3
	s_and_b32 s98, s2, 7
	s_and_b32 s14, s99, 3
	s_lshr_b32 s20, s99, 2
	s_lshr_b32 s100, s98, 1
	s_lshl_b32 s100, s100, 2
	s_add_i32 s14, s14, s100
	s_add_i32 s14, s14, 0
	s_and_b32 s100, s98, 1
	s_lshl_b32 s100, s100, 3
	s_add_i32 s20, s20, s100

.LBB0_248:
	s_add_i32 s90, s90, 1
	s_mul_i32 s3, s90, s80
	s_mul_hi_u32 s12, s90, s81
	s_add_i32 s12, s12, s3
	s_mul_i32 s3, s90, s81
	s_add_u32 s62, s3, s2
	s_addc_u32 s63, s12, s82
	v_cmp_gt_i64_e32 vcc, s[62:63], v[174:175]
	v_cmp_lt_i64_e64 s[12:13], s[62:63], v[172:173]
	s_cbranch_vccnz .LBB0_254
	s_cmp_eq_u32 s42, 0x100
	s_cbranch_scc0 .Lwgm_orig_1
	s_and_b32 s98, s2, 7
	s_lshr_b32 s99, s2, 3
	s_mov_b32 s100, s90
	s_lshl_b32 s100, s100, 4
	s_lshr_b32 s101, s98, 1
	s_lshl_b32 s101, s101, 2
	s_add_i32 s100, s100, s101
	s_and_b32 s101, s99, 3
	s_add_i32 s60, s100, s101
	s_and_b32 s100, s98, 1
	s_lshl_b32 s100, s100, 3
	s_lshr_b32 s101, s99, 2
	s_add_i32 s58, s100, s101
	s_branch .LBB0_254
